# v69 + nt on the scan's write-through o_a stores
# speedup vs baseline: 1.0352x; 1.0004x over previous
.Lpub_none:
	s_and_saveexec_b64 s[24:25], s[22:23]
	s_cbranch_execz .LBB0_583
	ds_read_b128 v[20:23], v149 offset:56320
	ds_read_b128 v[24:27], v149 offset:56336
	ds_read2st64_b32 v[8:9], v150 offset1:1
	ds_read_b128 v[28:31], v151 offset:9216
	ds_read_b128 v[32:35], v152
	v_add_u32_e32 v87, 0x14800, v106
	ds_read_b128 v[36:39], v87 offset:2304
	ds_read_b128 v[40:43], v87 offset:2320
	ds_read_b128 v[82:85], v87 offset:2560
	ds_read_b128 v[158:161], v87 offset:2576
	s_waitcnt lgkmcnt(6)
	v_add_f32_e32 v11, 0, v20
	v_add_f32_e32 v8, v8, v9
	v_add_f32_e32 v9, v21, v11
	v_add_f32_e32 v9, v22, v9
	v_add_f32_e32 v9, v23, v9
	v_add_f32_e32 v9, v24, v9
	v_add_f32_e32 v9, v25, v9
	v_add_f32_e32 v9, v26, v9
	v_add_f32_e32 v9, v27, v9
	s_waitcnt lgkmcnt(4)
	v_cvt_f32_f16_e32 v164, v28
	v_cvt_f32_f16_sdwa v165, v28 dst_sel:DWORD dst_unused:UNUSED_PAD src0_sel:WORD_1
	v_add_f32_dpp v9, v9, v9 quad_perm:[1,0,3,2] row_mask:0xf bank_mask:0xf bound_ctrl:1
	v_cvt_f32_f16_e32 v28, v29
	v_cvt_f32_f16_sdwa v29, v29 dst_sel:DWORD dst_unused:UNUSED_PAD src0_sel:WORD_1
	v_add_f32_dpp v9, v9, v9 quad_perm:[2,3,0,1] row_mask:0xf bank_mask:0xf bound_ctrl:1
	v_cvt_f32_f16_e32 v166, v32
	v_cvt_f32_f16_sdwa v167, v32 dst_sel:DWORD dst_unused:UNUSED_PAD src0_sel:WORD_1
	v_add_f32_dpp v9, v9, v9 row_half_mirror row_mask:0xf bank_mask:0xf bound_ctrl:1
	v_mul_f32_e32 v86, 0x3c800000, v9
	v_pk_add_f32 v[20:21], v[20:21], v[86:87] op_sel_hi:[1,0] neg_lo:[0,1] neg_hi:[0,1]
	v_pk_mul_f32 v[162:163], v[20:21], v[20:21]
	v_pk_add_f32 v[22:23], v[22:23], v[86:87] op_sel_hi:[1,0] neg_lo:[0,1] neg_hi:[0,1]
	v_pk_mul_f32 v[168:169], v[22:23], v[22:23]
	v_add_f32_e32 v9, v162, v163
	v_pk_add_f32 v[24:25], v[24:25], v[86:87] op_sel_hi:[1,0] neg_lo:[0,1] neg_hi:[0,1]
	v_add_f32_e32 v9, v168, v9
	v_pk_mul_f32 v[170:171], v[24:25], v[24:25]
	v_add_f32_e32 v9, v169, v9
	v_pk_add_f32 v[26:27], v[26:27], v[86:87] op_sel_hi:[1,0] neg_lo:[0,1] neg_hi:[0,1]
	v_add_f32_e32 v9, v170, v9
	v_pk_mul_f32 v[86:87], v[26:27], v[26:27]
	v_add_f32_e32 v9, v171, v9
	v_add_f32_e32 v9, v86, v9
	v_add_f32_e32 v9, v87, v9
	v_cvt_f32_f16_e32 v32, v33
	v_cvt_f32_f16_sdwa v33, v33 dst_sel:DWORD dst_unused:UNUSED_PAD src0_sel:WORD_1
	v_add_f32_dpp v9, v9, v9 quad_perm:[1,0,3,2] row_mask:0xf bank_mask:0xf bound_ctrl:1
	v_cvt_f32_f16_e32 v172, v30
	v_cvt_f32_f16_sdwa v173, v30 dst_sel:DWORD dst_unused:UNUSED_PAD src0_sel:WORD_1
	v_add_f32_dpp v9, v9, v9 quad_perm:[2,3,0,1] row_mask:0xf bank_mask:0xf bound_ctrl:1
	v_cvt_f32_f16_e32 v162, v34
	v_cvt_f32_f16_sdwa v163, v34 dst_sel:DWORD dst_unused:UNUSED_PAD src0_sel:WORD_1
	v_add_f32_dpp v9, v9, v9 row_half_mirror row_mask:0xf bank_mask:0xf bound_ctrl:1
	v_fmamk_f32 v9, v9, 0x3c800000, v153
	v_rsq_f32_e32 v86, v9
	s_nop 0
	v_pk_mul_f32 v[20:21], v[20:21], v[86:87] op_sel_hi:[1,0]
	v_pk_mul_f32 v[22:23], v[22:23], v[86:87] op_sel_hi:[1,0]
	s_waitcnt lgkmcnt(0)
	v_pk_fma_f32 v[20:21], v[36:37], v[20:21], v[82:83]
	v_pk_fma_f32 v[22:23], v[38:39], v[22:23], v[84:85]
	v_pk_fma_f32 v[20:21], v[8:9], v[164:165], v[20:21] op_sel_hi:[0,1,1]
	v_pk_fma_f32 v[22:23], v[8:9], v[28:29], v[22:23] op_sel_hi:[0,1,1]
	v_pk_mul_f32 v[20:21], v[20:21], v[166:167]
	v_pk_mul_f32 v[22:23], v[22:23], v[32:33]
	v_cvt_pk_f16_f32 v20, v20, v21
	v_cvt_pk_f16_f32 v21, v22, v23
	v_pk_mul_f32 v[22:23], v[24:25], v[86:87] op_sel_hi:[1,0]
	v_cvt_f32_f16_e32 v24, v31
	v_cvt_f32_f16_sdwa v25, v31 dst_sel:DWORD dst_unused:UNUSED_PAD src0_sel:WORD_1
	v_cvt_f32_f16_e32 v28, v35
	v_cvt_f32_f16_sdwa v29, v35 dst_sel:DWORD dst_unused:UNUSED_PAD src0_sel:WORD_1
	v_pk_mul_f32 v[26:27], v[26:27], v[86:87] op_sel_hi:[1,0]
	v_pk_fma_f32 v[22:23], v[40:41], v[22:23], v[158:159]
	v_pk_fma_f32 v[26:27], v[42:43], v[26:27], v[160:161]
	v_pk_fma_f32 v[22:23], v[8:9], v[172:173], v[22:23] op_sel_hi:[0,1,1]
	v_pk_fma_f32 v[8:9], v[8:9], v[24:25], v[26:27] op_sel_hi:[0,1,1]
	v_pk_mul_f32 v[22:23], v[22:23], v[162:163]
	v_pk_mul_f32 v[8:9], v[8:9], v[28:29]
	v_cvt_pk_f16_f32 v22, v22, v23
	v_cvt_pk_f16_f32 v23, v8, v9
	v_add_u32_e32 v8, s29, v107
	v_ashrrev_i32_e32 v9, 31, v8
	v_lshlrev_b64 v[8:9], 11, v[8:9]
	v_lshl_add_u64 v[8:9], v[60:61], 0, v[8:9]
	global_store_dwordx4 v[8:9], v[20:23], off sc1 nt
	s_nop 1

.Lsz_skip:
	s_barrier
	s_and_saveexec_b64 s[24:25], s[22:23]
	s_cbranch_execz .Lds_e583
	ds_read_b128 v[20:23], v149 offset:56320
	ds_read_b128 v[24:27], v149 offset:56336
	ds_read2st64_b32 v[8:9], v150 offset1:1
	ds_read_b128 v[28:31], v151 offset:9216
	ds_read_b128 v[32:35], v152
	v_add_u32_e32 v87, 0x14800, v106
	ds_read_b128 v[36:39], v87 offset:2304
	ds_read_b128 v[40:43], v87 offset:2320
	ds_read_b128 v[82:85], v87 offset:2560
	ds_read_b128 v[158:161], v87 offset:2576
	s_waitcnt lgkmcnt(6)
	v_add_f32_e32 v11, 0, v20
	v_add_f32_e32 v8, v8, v9
	v_add_f32_e32 v9, v21, v11
	v_add_f32_e32 v9, v22, v9
	v_add_f32_e32 v9, v23, v9
	v_add_f32_e32 v9, v24, v9
	v_add_f32_e32 v9, v25, v9
	v_add_f32_e32 v9, v26, v9
	v_add_f32_e32 v9, v27, v9
	s_waitcnt lgkmcnt(4)
	v_cvt_f32_f16_e32 v164, v28
	v_cvt_f32_f16_sdwa v165, v28 dst_sel:DWORD dst_unused:UNUSED_PAD src0_sel:WORD_1
	v_add_f32_dpp v9, v9, v9 quad_perm:[1,0,3,2] row_mask:0xf bank_mask:0xf bound_ctrl:1
	v_cvt_f32_f16_e32 v28, v29
	v_cvt_f32_f16_sdwa v29, v29 dst_sel:DWORD dst_unused:UNUSED_PAD src0_sel:WORD_1
	v_add_f32_dpp v9, v9, v9 quad_perm:[2,3,0,1] row_mask:0xf bank_mask:0xf bound_ctrl:1
	v_cvt_f32_f16_e32 v166, v32
	v_cvt_f32_f16_sdwa v167, v32 dst_sel:DWORD dst_unused:UNUSED_PAD src0_sel:WORD_1
	v_add_f32_dpp v9, v9, v9 row_half_mirror row_mask:0xf bank_mask:0xf bound_ctrl:1
	v_mul_f32_e32 v86, 0x3c800000, v9
	v_pk_add_f32 v[20:21], v[20:21], v[86:87] op_sel_hi:[1,0] neg_lo:[0,1] neg_hi:[0,1]
	v_pk_mul_f32 v[162:163], v[20:21], v[20:21]
	v_pk_add_f32 v[22:23], v[22:23], v[86:87] op_sel_hi:[1,0] neg_lo:[0,1] neg_hi:[0,1]
	v_pk_mul_f32 v[168:169], v[22:23], v[22:23]
	v_add_f32_e32 v9, v162, v163
	v_pk_add_f32 v[24:25], v[24:25], v[86:87] op_sel_hi:[1,0] neg_lo:[0,1] neg_hi:[0,1]
	v_add_f32_e32 v9, v168, v9
	v_pk_mul_f32 v[170:171], v[24:25], v[24:25]
	v_add_f32_e32 v9, v169, v9
	v_pk_add_f32 v[26:27], v[26:27], v[86:87] op_sel_hi:[1,0] neg_lo:[0,1] neg_hi:[0,1]
	v_add_f32_e32 v9, v170, v9
	v_pk_mul_f32 v[86:87], v[26:27], v[26:27]
	v_add_f32_e32 v9, v171, v9
	v_add_f32_e32 v9, v86, v9
	v_add_f32_e32 v9, v87, v9
	v_cvt_f32_f16_e32 v32, v33
	v_cvt_f32_f16_sdwa v33, v33 dst_sel:DWORD dst_unused:UNUSED_PAD src0_sel:WORD_1
	v_add_f32_dpp v9, v9, v9 quad_perm:[1,0,3,2] row_mask:0xf bank_mask:0xf bound_ctrl:1
	v_cvt_f32_f16_e32 v172, v30
	v_cvt_f32_f16_sdwa v173, v30 dst_sel:DWORD dst_unused:UNUSED_PAD src0_sel:WORD_1
	v_add_f32_dpp v9, v9, v9 quad_perm:[2,3,0,1] row_mask:0xf bank_mask:0xf bound_ctrl:1
	v_cvt_f32_f16_e32 v162, v34
	v_cvt_f32_f16_sdwa v163, v34 dst_sel:DWORD dst_unused:UNUSED_PAD src0_sel:WORD_1
	v_add_f32_dpp v9, v9, v9 row_half_mirror row_mask:0xf bank_mask:0xf bound_ctrl:1
	v_fmamk_f32 v9, v9, 0x3c800000, v153
	v_rsq_f32_e32 v86, v9
	s_nop 0
	v_pk_mul_f32 v[20:21], v[20:21], v[86:87] op_sel_hi:[1,0]
	v_pk_mul_f32 v[22:23], v[22:23], v[86:87] op_sel_hi:[1,0]
	s_waitcnt lgkmcnt(0)
	v_pk_fma_f32 v[20:21], v[36:37], v[20:21], v[82:83]
	v_pk_fma_f32 v[22:23], v[38:39], v[22:23], v[84:85]
	v_pk_fma_f32 v[20:21], v[8:9], v[164:165], v[20:21] op_sel_hi:[0,1,1]
	v_pk_fma_f32 v[22:23], v[8:9], v[28:29], v[22:23] op_sel_hi:[0,1,1]
	v_pk_mul_f32 v[20:21], v[20:21], v[166:167]
	v_pk_mul_f32 v[22:23], v[22:23], v[32:33]
	v_cvt_pk_f16_f32 v20, v20, v21
	v_cvt_pk_f16_f32 v21, v22, v23
	v_pk_mul_f32 v[22:23], v[24:25], v[86:87] op_sel_hi:[1,0]
	v_cvt_f32_f16_e32 v24, v31
	v_cvt_f32_f16_sdwa v25, v31 dst_sel:DWORD dst_unused:UNUSED_PAD src0_sel:WORD_1
	v_cvt_f32_f16_e32 v28, v35
	v_cvt_f32_f16_sdwa v29, v35 dst_sel:DWORD dst_unused:UNUSED_PAD src0_sel:WORD_1
	v_pk_mul_f32 v[26:27], v[26:27], v[86:87] op_sel_hi:[1,0]
	v_pk_fma_f32 v[22:23], v[40:41], v[22:23], v[158:159]
	v_pk_fma_f32 v[26:27], v[42:43], v[26:27], v[160:161]
	v_pk_fma_f32 v[22:23], v[8:9], v[172:173], v[22:23] op_sel_hi:[0,1,1]
	v_pk_fma_f32 v[8:9], v[8:9], v[24:25], v[26:27] op_sel_hi:[0,1,1]
	v_pk_mul_f32 v[22:23], v[22:23], v[162:163]
	v_pk_mul_f32 v[8:9], v[8:9], v[28:29]
	v_cvt_pk_f16_f32 v22, v22, v23
	v_cvt_pk_f16_f32 v23, v8, v9
	v_add_u32_e32 v8, s29, v107
	v_ashrrev_i32_e32 v9, 31, v8
	v_lshlrev_b64 v[8:9], 11, v[8:9]
	v_lshl_add_u64 v[8:9], v[60:61], 0, v[8:9]
	global_store_dwordx4 v[8:9], v[20:23], off sc1 nt
	s_nop 1
